# k46 + write-through (sc1) stores in the first phase (normalised x rows, weight transposes) so the first grid barrier's L2 writeback has less dirty data
# speedup vs baseline: 1.0228x; 1.0228x over previous
.LBB0_20:
	v_lshl_add_u64 v[42:43], v[26:27], 0, s[22:23]
	v_lshl_add_u64 v[44:45], v[24:25], 0, s[22:23]
	v_lshl_add_u64 v[46:47], v[22:23], 0, s[22:23]
	v_lshl_add_u64 v[48:49], v[20:21], 0, s[22:23]
	v_lshl_add_u64 v[50:51], v[18:19], 0, s[22:23]
	v_lshl_add_u64 v[52:53], v[16:17], 0, s[22:23]
	v_lshl_add_u64 v[54:55], v[14:15], 0, s[22:23]
	v_lshl_add_u64 v[56:57], v[12:13], 0, s[22:23]
	global_load_dword v58, v[42:43], off nt
	global_load_dword v59, v[44:45], off nt
	global_load_dword v60, v[46:47], off nt
	global_load_dword v61, v[48:49], off nt
	global_load_dword v62, v[50:51], off nt
	global_load_dword v63, v[52:53], off nt
	global_load_dword v64, v[54:55], off nt
	global_load_dword v65, v[56:57], off nt
	s_add_u32 s22, s22, 0x10000
	s_addc_u32 s23, s23, 0
	v_add_u32_e32 v42, 0x400, v41
	s_cmp_lg_u32 s22, 0x40000
	s_waitcnt vmcnt(6)
	ds_write2_b32 v41, v58, v59 offset1:66
	s_waitcnt vmcnt(4)
	ds_write2_b32 v41, v60, v61 offset0:132 offset1:198
	s_waitcnt vmcnt(2)
	ds_write2_b32 v42, v62, v63 offset0:8 offset1:74
	s_waitcnt vmcnt(0)
	ds_write2_b32 v42, v64, v65 offset0:140 offset1:206
	v_add_u32_e32 v41, 0x840, v41
	s_cbranch_scc1 .LBB0_20
	s_waitcnt lgkmcnt(0)
	ds_read2_b32 v[16:17], v28 offset1:8
	ds_read2_b32 v[20:21], v28 offset0:33 offset1:41
	ds_read2_b32 v[22:23], v28 offset0:66 offset1:74
	ds_read2_b32 v[24:25], v28 offset0:99 offset1:107
	ds_read2_b32 v[26:27], v28 offset0:132 offset1:140
	s_waitcnt lgkmcnt(4)
	v_bfe_u32 v12, v16, 16, 1
	v_add3_u32 v12, v16, v12, s26
	s_waitcnt lgkmcnt(3)
	v_bfe_u32 v13, v20, 16, 1
	v_lshrrev_b32_e32 v12, 16, v12
	v_add3_u32 v13, v20, v13, s26
	ds_read2_b32 v[42:43], v28 offset0:165 offset1:173
	v_and_or_b32 v12, v13, s27, v12
	s_waitcnt lgkmcnt(3)
	v_bfe_u32 v13, v22, 16, 1
	v_add3_u32 v13, v22, v13, s26
	s_waitcnt lgkmcnt(2)
	v_bfe_u32 v14, v24, 16, 1
	ds_read2_b32 v[44:45], v28 offset0:198 offset1:206
	v_lshrrev_b32_e32 v13, 16, v13
	v_add3_u32 v14, v24, v14, s26
	ds_read2_b32 v[46:47], v28 offset0:231 offset1:239
	v_and_or_b32 v13, v14, s27, v13
	s_waitcnt lgkmcnt(3)
	v_bfe_u32 v14, v26, 16, 1
	v_add3_u32 v14, v26, v14, s26
	s_waitcnt lgkmcnt(2)
	v_bfe_u32 v15, v42, 16, 1
	v_lshrrev_b32_e32 v14, 16, v14
	v_add3_u32 v15, v42, v15, s26
	v_and_or_b32 v14, v15, s27, v14
	s_waitcnt lgkmcnt(1)
	v_bfe_u32 v15, v44, 16, 1
	s_lshl_b32 s20, s29, 1
	s_lshl_b32 s22, s29, 5
	v_add3_u32 v15, v44, v15, s26
	s_waitcnt lgkmcnt(0)
	v_bfe_u32 v16, v46, 16, 1
	s_and_b32 s20, s20, 0x7fffffc0
	s_and_b32 s22, s22, 0x3e0
	v_lshrrev_b32_e32 v15, 16, v15
	v_add3_u32 v16, v46, v16, s26
	s_addk_i32 s20, 0xf600
	v_and_or_b32 v15, v16, s27, v15
	v_or_b32_e32 v16, s22, v3
	v_lshl_add_u64 v[18:19], s[20:21], 1, v[6:7]
	v_lshlrev_b32_e32 v48, 9, v16
	v_mov_b32_e32 v49, v5
	v_lshl_add_u64 v[48:49], v[18:19], 0, v[48:49]
	global_store_dwordx4 v[48:49], v[12:15], off sc1
	v_bfe_u32 v16, v47, 16, 1
	v_add3_u32 v16, v47, v16, s26
	v_bfe_u32 v12, v17, 16, 1
	v_add3_u32 v12, v17, v12, s26
	v_bfe_u32 v13, v21, 16, 1
	v_lshrrev_b32_e32 v12, 16, v12
	v_add3_u32 v13, v21, v13, s26
	v_and_or_b32 v12, v13, s27, v12
	v_bfe_u32 v13, v23, 16, 1
	v_add3_u32 v13, v23, v13, s26
	v_bfe_u32 v14, v25, 16, 1
	v_lshrrev_b32_e32 v13, 16, v13
	v_add3_u32 v14, v25, v14, s26
	v_and_or_b32 v13, v14, s27, v13
	v_bfe_u32 v14, v27, 16, 1
	v_add3_u32 v14, v27, v14, s26
	v_bfe_u32 v15, v43, 16, 1
	v_lshrrev_b32_e32 v14, 16, v14
	v_add3_u32 v15, v43, v15, s26
	v_and_or_b32 v14, v15, s27, v14
	v_bfe_u32 v15, v45, 16, 1
	v_add3_u32 v15, v45, v15, s26
	v_lshrrev_b32_e32 v15, 16, v15
	v_and_or_b32 v15, v16, s27, v15
	v_or_b32_e32 v16, s22, v29
	v_lshlrev_b32_e32 v16, 9, v16
	v_mov_b32_e32 v17, v5
	ds_read2_b32 v[20:21], v28 offset0:16 offset1:24
	v_lshl_add_u64 v[16:17], v[18:19], 0, v[16:17]
	global_store_dwordx4 v[16:17], v[12:15], off sc1
	ds_read2_b32 v[16:17], v28 offset0:49 offset1:57
	ds_read2_b32 v[22:23], v28 offset0:82 offset1:90
	ds_read2_b32 v[24:25], v28 offset0:115 offset1:123
	s_waitcnt lgkmcnt(3)
	v_bfe_u32 v12, v20, 16, 1
	v_add3_u32 v12, v20, v12, s26
	s_waitcnt lgkmcnt(2)
	v_bfe_u32 v13, v16, 16, 1
	ds_read2_b32 v[26:27], v28 offset0:148 offset1:156
	v_lshrrev_b32_e32 v12, 16, v12
	v_add3_u32 v13, v16, v13, s26
	ds_read2_b32 v[42:43], v28 offset0:181 offset1:189
	v_and_or_b32 v12, v13, s27, v12
	s_waitcnt lgkmcnt(3)
	v_bfe_u32 v13, v22, 16, 1
	v_add3_u32 v13, v22, v13, s26
	s_waitcnt lgkmcnt(2)
	v_bfe_u32 v14, v24, 16, 1
	ds_read2_b32 v[44:45], v28 offset0:214 offset1:222
	v_lshrrev_b32_e32 v13, 16, v13
	v_add3_u32 v14, v24, v14, s26
	ds_read2_b32 v[46:47], v28 offset0:247 offset1:255
	v_and_or_b32 v13, v14, s27, v13
	s_waitcnt lgkmcnt(3)
	v_bfe_u32 v14, v26, 16, 1
	v_add3_u32 v14, v26, v14, s26
	s_waitcnt lgkmcnt(2)
	v_bfe_u32 v15, v42, 16, 1
	v_lshrrev_b32_e32 v14, 16, v14
	v_add3_u32 v15, v42, v15, s26
	v_and_or_b32 v14, v15, s27, v14
	s_waitcnt lgkmcnt(1)
	v_bfe_u32 v15, v44, 16, 1
	v_add3_u32 v15, v44, v15, s26
	s_waitcnt lgkmcnt(0)
	v_bfe_u32 v16, v46, 16, 1
	v_lshrrev_b32_e32 v15, 16, v15
	v_add3_u32 v16, v46, v16, s26
	v_and_or_b32 v15, v16, s27, v15
	v_or_b32_e32 v16, s22, v30
	v_lshlrev_b32_e32 v48, 9, v16
	v_mov_b32_e32 v49, v5
	v_lshl_add_u64 v[48:49], v[18:19], 0, v[48:49]
	global_store_dwordx4 v[48:49], v[12:15], off sc1
	v_bfe_u32 v16, v47, 16, 1
	v_add3_u32 v16, v47, v16, s26
	v_bfe_u32 v12, v21, 16, 1
	v_add3_u32 v12, v21, v12, s26
	v_bfe_u32 v13, v17, 16, 1
	v_lshrrev_b32_e32 v12, 16, v12
	v_add3_u32 v13, v17, v13, s26
	v_and_or_b32 v12, v13, s27, v12
	v_bfe_u32 v13, v23, 16, 1
	v_add3_u32 v13, v23, v13, s26
	v_bfe_u32 v14, v25, 16, 1
	v_lshrrev_b32_e32 v13, 16, v13
	v_add3_u32 v14, v25, v14, s26
	v_and_or_b32 v13, v14, s27, v13
	v_bfe_u32 v14, v27, 16, 1
	v_add3_u32 v14, v27, v14, s26
	v_bfe_u32 v15, v43, 16, 1
	v_lshrrev_b32_e32 v14, 16, v14
	v_add3_u32 v15, v43, v15, s26
	v_and_or_b32 v14, v15, s27, v14
	v_bfe_u32 v15, v45, 16, 1
	v_add3_u32 v15, v45, v15, s26
	v_lshrrev_b32_e32 v15, 16, v15
	v_and_or_b32 v15, v16, s27, v15
	v_or_b32_e32 v16, s22, v31
	v_lshlrev_b32_e32 v16, 9, v16
	v_mov_b32_e32 v17, v5
	v_lshl_add_u64 v[16:17], v[18:19], 0, v[16:17]
	global_store_dwordx4 v[16:17], v[12:15], off sc1
	s_waitcnt lgkmcnt(0)
	s_mov_b64 s[22:23], 0

.LBB0_29:
	v_add_u32_e32 v18, s23, v14
	v_mad_i64_i32 v[16:17], s[30:31], v18, s28, v[12:13]
	v_add_u32_e32 v19, 2, v18
	v_add_u32_e32 v20, 4, v18
	v_add_u32_e32 v22, 6, v18
	v_add_u32_e32 v24, 8, v18
	v_add_u32_e32 v26, 10, v18
	v_add_u32_e32 v41, 12, v18
	v_add_u32_e32 v44, 14, v18
	v_mad_i64_i32 v[18:19], s[30:31], v19, s28, v[12:13]
	v_mad_i64_i32 v[20:21], s[30:31], v20, s28, v[12:13]
	v_mad_i64_i32 v[22:23], s[30:31], v22, s28, v[12:13]
	v_mad_i64_i32 v[24:25], s[30:31], v24, s28, v[12:13]
	v_mad_i64_i32 v[26:27], s[30:31], v26, s28, v[12:13]
	v_mad_i64_i32 v[42:43], s[30:31], v41, s28, v[12:13]
	v_mad_i64_i32 v[44:45], s[30:31], v44, s28, v[12:13]
	global_load_dword v41, v[16:17], off nt
	global_load_dword v46, v[18:19], off nt
	global_load_dword v47, v[20:21], off nt
	global_load_dword v48, v[22:23], off nt
	global_load_dword v49, v[24:25], off nt
	global_load_dword v50, v[26:27], off nt
	global_load_dword v51, v[42:43], off nt
	global_load_dword v52, v[44:45], off nt
	s_add_i32 s23, s23, 16
	v_add_u32_e32 v16, 0x400, v15
	s_cmp_lg_u32 s23, 64
	s_waitcnt vmcnt(6)
	ds_write2_b32 v15, v41, v46 offset1:66
	s_waitcnt vmcnt(4)
	ds_write2_b32 v15, v47, v48 offset0:132 offset1:198
	s_waitcnt vmcnt(2)
	ds_write2_b32 v16, v49, v50 offset0:8 offset1:74
	s_waitcnt vmcnt(0)
	ds_write2_b32 v16, v51, v52 offset0:140 offset1:206
	v_add_u32_e32 v15, 0x840, v15
	s_cbranch_scc1 .LBB0_29
	s_waitcnt lgkmcnt(0)
	ds_read2_b32 v[16:17], v28 offset1:8
	ds_read2_b32 v[20:21], v28 offset0:33 offset1:41
	ds_read2_b32 v[22:23], v28 offset0:66 offset1:74
	ds_read2_b32 v[24:25], v28 offset0:99 offset1:107
	ds_read2_b32 v[26:27], v28 offset0:132 offset1:140
	ds_read2_b32 v[42:43], v28 offset0:165 offset1:173
	s_waitcnt lgkmcnt(5)
	v_bfe_u32 v12, v16, 16, 1
	v_add3_u32 v12, v16, v12, s26
	s_waitcnt lgkmcnt(4)
	v_bfe_u32 v13, v20, 16, 1
	v_lshrrev_b32_e32 v12, 16, v12
	v_add3_u32 v13, v20, v13, s26
	v_and_or_b32 v12, v13, s27, v12
	s_waitcnt lgkmcnt(3)
	v_bfe_u32 v13, v22, 16, 1
	v_add3_u32 v13, v22, v13, s26
	s_waitcnt lgkmcnt(2)
	v_bfe_u32 v14, v24, 16, 1
	ds_read2_b32 v[44:45], v28 offset0:198 offset1:206
	v_lshrrev_b32_e32 v13, 16, v13
	v_add3_u32 v14, v24, v14, s26
	ds_read2_b32 v[46:47], v28 offset0:231 offset1:239
	v_and_or_b32 v13, v14, s27, v13
	s_waitcnt lgkmcnt(3)
	v_bfe_u32 v14, v26, 16, 1
	v_add3_u32 v14, v26, v14, s26
	s_waitcnt lgkmcnt(2)
	v_bfe_u32 v15, v42, 16, 1
	v_lshrrev_b32_e32 v14, 16, v14
	v_add3_u32 v15, v42, v15, s26
	v_and_or_b32 v14, v15, s27, v14
	s_waitcnt lgkmcnt(1)
	v_bfe_u32 v15, v44, 16, 1
	v_add_u32_e32 v48, s20, v3
	s_ashr_i32 s23, s22, 31
	v_add3_u32 v15, v44, v15, s26
	s_waitcnt lgkmcnt(0)
	v_bfe_u32 v16, v46, 16, 1
	v_ashrrev_i32_e32 v49, 31, v48
	v_lshl_add_u64 v[18:19], s[22:23], 1, v[8:9]
	v_lshrrev_b32_e32 v15, 16, v15
	v_add3_u32 v16, v46, v16, s26
	v_lshlrev_b64 v[48:49], 11, v[48:49]
	v_and_or_b32 v15, v16, s27, v15
	v_lshl_add_u64 v[48:49], v[18:19], 0, v[48:49]
	global_store_dwordx4 v[48:49], v[12:15], off sc1
	v_bfe_u32 v16, v47, 16, 1
	v_add3_u32 v16, v47, v16, s26
	v_bfe_u32 v12, v17, 16, 1
	v_add3_u32 v12, v17, v12, s26
	v_bfe_u32 v13, v21, 16, 1
	v_lshrrev_b32_e32 v12, 16, v12
	v_add3_u32 v13, v21, v13, s26
	v_and_or_b32 v12, v13, s27, v12
	v_bfe_u32 v13, v23, 16, 1
	v_add3_u32 v13, v23, v13, s26
	v_bfe_u32 v14, v25, 16, 1
	v_lshrrev_b32_e32 v13, 16, v13
	v_add3_u32 v14, v25, v14, s26
	v_and_or_b32 v13, v14, s27, v13
	v_bfe_u32 v14, v27, 16, 1
	v_add3_u32 v14, v27, v14, s26
	v_bfe_u32 v15, v43, 16, 1
	v_lshrrev_b32_e32 v14, 16, v14
	v_add3_u32 v15, v43, v15, s26
	v_and_or_b32 v14, v15, s27, v14
	v_bfe_u32 v15, v45, 16, 1
	v_add3_u32 v15, v45, v15, s26
	v_lshrrev_b32_e32 v15, 16, v15
	v_and_or_b32 v15, v16, s27, v15
	v_add_u32_e32 v16, s20, v29
	v_ashrrev_i32_e32 v17, 31, v16
	v_lshlrev_b64 v[16:17], 11, v[16:17]
	ds_read2_b32 v[20:21], v28 offset0:16 offset1:24
	v_lshl_add_u64 v[16:17], v[18:19], 0, v[16:17]
	global_store_dwordx4 v[16:17], v[12:15], off sc1
	ds_read2_b32 v[16:17], v28 offset0:49 offset1:57
	ds_read2_b32 v[22:23], v28 offset0:82 offset1:90
	ds_read2_b32 v[24:25], v28 offset0:115 offset1:123
	s_waitcnt lgkmcnt(3)
	v_bfe_u32 v12, v20, 16, 1
	v_add3_u32 v12, v20, v12, s26
	s_waitcnt lgkmcnt(2)
	v_bfe_u32 v13, v16, 16, 1
	ds_read2_b32 v[26:27], v28 offset0:148 offset1:156
	v_lshrrev_b32_e32 v12, 16, v12
	v_add3_u32 v13, v16, v13, s26
	ds_read2_b32 v[42:43], v28 offset0:181 offset1:189
	v_and_or_b32 v12, v13, s27, v12
	s_waitcnt lgkmcnt(3)
	v_bfe_u32 v13, v22, 16, 1
	v_add3_u32 v13, v22, v13, s26
	s_waitcnt lgkmcnt(2)
	v_bfe_u32 v14, v24, 16, 1
	ds_read2_b32 v[44:45], v28 offset0:214 offset1:222
	v_lshrrev_b32_e32 v13, 16, v13
	v_add3_u32 v14, v24, v14, s26
	ds_read2_b32 v[46:47], v28 offset0:247 offset1:255
	v_and_or_b32 v13, v14, s27, v13
	s_waitcnt lgkmcnt(3)
	v_bfe_u32 v14, v26, 16, 1
	v_add3_u32 v14, v26, v14, s26
	s_waitcnt lgkmcnt(2)
	v_bfe_u32 v15, v42, 16, 1
	v_lshrrev_b32_e32 v14, 16, v14
	v_add3_u32 v15, v42, v15, s26
	v_and_or_b32 v14, v15, s27, v14
	s_waitcnt lgkmcnt(1)
	v_bfe_u32 v15, v44, 16, 1
	v_add_u32_e32 v48, s20, v30
	v_add3_u32 v15, v44, v15, s26
	s_waitcnt lgkmcnt(0)
	v_bfe_u32 v16, v46, 16, 1
	v_ashrrev_i32_e32 v49, 31, v48
	v_lshrrev_b32_e32 v15, 16, v15
	v_add3_u32 v16, v46, v16, s26
	v_lshlrev_b64 v[48:49], 11, v[48:49]
	v_and_or_b32 v15, v16, s27, v15
	v_lshl_add_u64 v[48:49], v[18:19], 0, v[48:49]
	global_store_dwordx4 v[48:49], v[12:15], off sc1
	v_bfe_u32 v16, v47, 16, 1
	v_add3_u32 v16, v47, v16, s26
	v_bfe_u32 v12, v21, 16, 1
	v_add3_u32 v12, v21, v12, s26
	v_bfe_u32 v13, v17, 16, 1
	v_lshrrev_b32_e32 v12, 16, v12
	v_add3_u32 v13, v17, v13, s26
	v_and_or_b32 v12, v13, s27, v12
	v_bfe_u32 v13, v23, 16, 1
	v_add3_u32 v13, v23, v13, s26
	v_bfe_u32 v14, v25, 16, 1
	v_lshrrev_b32_e32 v13, 16, v13
	v_add3_u32 v14, v25, v14, s26
	v_and_or_b32 v13, v14, s27, v13
	v_bfe_u32 v14, v27, 16, 1
	v_add3_u32 v14, v27, v14, s26
	v_bfe_u32 v15, v43, 16, 1
	v_lshrrev_b32_e32 v14, 16, v14
	v_add3_u32 v15, v43, v15, s26
	v_and_or_b32 v14, v15, s27, v14
	v_bfe_u32 v15, v45, 16, 1
	v_add3_u32 v15, v45, v15, s26
	v_lshrrev_b32_e32 v15, 16, v15
	v_and_or_b32 v15, v16, s27, v15
	v_add_u32_e32 v16, s20, v31
	v_ashrrev_i32_e32 v17, 31, v16
	v_lshlrev_b64 v[16:17], 11, v[16:17]
	v_lshl_add_u64 v[16:17], v[18:19], 0, v[16:17]
	global_store_dwordx4 v[16:17], v[12:15], off sc1
	s_waitcnt lgkmcnt(0)
	s_branch .LBB0_17

.LBB0_33:
	s_add_i32 s38, s40, 0xffffc000
	s_lshl_b64 s[4:5], s[38:39], 10
	s_add_u32 s13, s6, s4
	s_addc_u32 s29, s7, s5
	s_cmpk_lt_i32 s40, 0x4000
	s_cselect_b32 s5, s41, 0
	s_cselect_b32 s4, s40, s38
	s_cselect_b32 s30, s9, s11
	s_cselect_b32 s31, s8, s10
	s_cselect_b32 s42, s3, s13
	s_cselect_b32 s43, s24, s29
	s_lshl_b64 s[4:5], s[4:5], 12
	v_lshl_add_u64 v[12:13], s[16:17], 0, v[0:1]
	s_add_u32 s4, s31, s4
	v_add_co_u32_e32 v28, vcc, s28, v12
	s_addc_u32 s5, s30, s5
	global_load_dwordx4 v[8:11], v[4:5], off
	v_addc_co_u32_e32 v29, vcc, 0, v13, vcc
	global_load_dwordx4 v[12:15], v2, s[4:5] nt
	global_load_dwordx4 v[16:19], v2, s[4:5] offset:1024 nt
	global_load_dwordx4 v[20:23], v2, s[4:5] offset:2048 nt
	global_load_dwordx4 v[24:27], v2, s[4:5] offset:3072 nt
	s_add_u32 s40, s40, s34
	s_addc_u32 s41, s41, s35
	s_add_u32 s16, s16, s18
	s_addc_u32 s17, s17, s19
	s_add_u32 s3, s3, s20
	s_addc_u32 s24, s24, s21
	s_waitcnt vmcnt(3)
	v_mul_f32_e32 v7, v13, v13
	v_mul_f32_e32 v30, v15, v15
	s_waitcnt vmcnt(2)
	v_mul_f32_e32 v31, v17, v17
	v_mul_f32_e32 v32, v19, v19
	s_waitcnt vmcnt(1)
	v_mul_f32_e32 v33, v21, v21
	v_mul_f32_e32 v34, v23, v23
	v_fmac_f32_e32 v7, v12, v12
	v_fmac_f32_e32 v30, v14, v14
	v_fmac_f32_e32 v31, v16, v16
	v_fmac_f32_e32 v32, v18, v18
	s_waitcnt vmcnt(0)
	v_mul_f32_e32 v35, v25, v25
	v_mul_f32_e32 v36, v27, v27
	v_fmac_f32_e32 v33, v20, v20
	v_fmac_f32_e32 v34, v22, v22
	v_add_f32_e32 v7, v7, v30
	v_add_f32_e32 v30, v31, v32
	v_fmac_f32_e32 v35, v24, v24
	v_fmac_f32_e32 v36, v26, v26
	v_add_f32_e32 v31, v33, v34
	v_add_f32_e32 v7, v7, v30
	v_add_f32_e32 v32, v35, v36
	v_add_f32_e32 v7, v7, v31
	v_add_f32_e32 v7, v7, v32
	s_nop 1
	v_add_f32_dpp v7, v7, v7 quad_perm:[1,0,3,2] row_mask:0xf bank_mask:0xf bound_ctrl:1
	s_nop 1
	v_add_f32_dpp v7, v7, v7 quad_perm:[2,3,0,1] row_mask:0xf bank_mask:0xf bound_ctrl:1
	s_nop 1
	v_add_f32_dpp v7, v7, v7 row_half_mirror row_mask:0xf bank_mask:0xf bound_ctrl:1
	s_nop 1
	v_add_f32_dpp v7, v7, v7 row_ror:8 row_mask:0xf bank_mask:0xf bound_ctrl:1
	v_mov_b32_e32 v30, v7
	s_nop 1
	v_permlane16_swap_b32_e32 v7, v30
	v_add_f32_e32 v7, v7, v30
	v_mov_b32_e32 v30, v7
	s_nop 1
	v_permlane32_swap_b32_e32 v7, v30
	v_add_f32_e32 v7, v7, v30
	v_fmamk_f32 v7, v7, 0x3a800000, v3
	v_mul_f32_e32 v30, 0x4f800000, v7
	v_cmp_gt_f32_e32 vcc, s25, v7
	s_nop 1
	v_cndmask_b32_e32 v7, v7, v30, vcc
	v_sqrt_f32_e32 v30, v7
	s_nop 0
	v_add_u32_e32 v31, -1, v30
	v_add_u32_e32 v32, 1, v30
	v_fma_f32 v33, -v31, v30, v7
	v_fma_f32 v34, -v32, v30, v7
	v_cmp_ge_f32_e64 s[4:5], 0, v33
	s_nop 1
	v_cndmask_b32_e64 v30, v30, v31, s[4:5]
	v_cmp_lt_f32_e64 s[4:5], 0, v34
	s_nop 1
	v_cndmask_b32_e64 v30, v30, v32, s[4:5]
	v_mul_f32_e32 v31, 0x37800000, v30
	v_cndmask_b32_e32 v30, v30, v31, vcc
	v_cmp_class_f32_e32 vcc, v7, v6
	s_nop 1
	v_cndmask_b32_e32 v7, v30, v7, vcc
	v_div_scale_f32 v30, s[4:5], v7, v7, 1.0
	v_rcp_f32_e32 v32, v30
	v_div_scale_f32 v31, vcc, 1.0, v7, 1.0
	v_fma_f32 v33, -v30, v32, 1.0
	v_fmac_f32_e32 v32, v33, v32
	v_mul_f32_e32 v33, v31, v32
	v_fma_f32 v34, -v30, v33, v31
	v_fmac_f32_e32 v33, v34, v32
	v_fma_f32 v30, -v30, v33, v31
	v_div_fmas_f32 v30, v30, v32, v33
	v_div_fixup_f32 v7, v30, v7, 1.0
	v_mul_f32_e32 v12, v12, v7
	v_mul_f32_e32 v14, v14, v7
	v_mul_f32_e32 v13, v13, v7
	v_mul_f32_e32 v15, v15, v7
	v_mul_f32_e32 v8, v8, v12
	v_mul_f32_e32 v10, v10, v14
	v_mul_f32_e32 v9, v9, v13
	v_mul_f32_e32 v11, v11, v15
	v_bfe_u32 v12, v8, 16, 1
	v_bfe_u32 v14, v10, 16, 1
	v_bfe_u32 v13, v9, 16, 1
	v_bfe_u32 v15, v11, 16, 1
	v_add3_u32 v8, v8, v12, s26
	v_add3_u32 v10, v10, v14, s26
	v_add3_u32 v9, v9, v13, s26
	v_add3_u32 v11, v11, v15, s26
	v_lshrrev_b32_e32 v8, 16, v8
	v_lshrrev_b32_e32 v10, 16, v10
	v_and_or_b32 v8, v9, s27, v8
	v_and_or_b32 v9, v11, s27, v10
	global_store_dwordx2 v[28:29], v[8:9], off sc1
	global_load_dwordx4 v[8:11], v[4:5], off offset:1024
	v_mul_f32_e32 v12, v16, v7
	v_mul_f32_e32 v14, v18, v7
	v_mul_f32_e32 v13, v17, v7
	v_mul_f32_e32 v15, v19, v7
	s_waitcnt vmcnt(0)
	v_mul_f32_e32 v8, v8, v12
	v_mul_f32_e32 v10, v10, v14
	v_mul_f32_e32 v9, v9, v13
	v_mul_f32_e32 v11, v11, v15
	v_bfe_u32 v12, v8, 16, 1
	v_bfe_u32 v14, v10, 16, 1
	v_bfe_u32 v13, v9, 16, 1
	v_bfe_u32 v15, v11, 16, 1
	v_add3_u32 v8, v8, v12, s26
	v_add3_u32 v10, v10, v14, s26
	v_add3_u32 v9, v9, v13, s26
	v_add3_u32 v11, v11, v15, s26
	v_lshrrev_b32_e32 v8, 16, v8
	v_lshrrev_b32_e32 v10, 16, v10
	v_and_or_b32 v8, v9, s27, v8
	v_and_or_b32 v9, v11, s27, v10
	global_store_dwordx2 v[28:29], v[8:9], off offset:512 sc1
	global_load_dwordx4 v[8:11], v[4:5], off offset:2048
	v_mul_f32_e32 v12, v20, v7
	v_mul_f32_e32 v14, v22, v7
	v_mul_f32_e32 v13, v21, v7
	v_mul_f32_e32 v15, v23, v7
	s_waitcnt vmcnt(0)
	v_mul_f32_e32 v8, v8, v12
	v_mul_f32_e32 v10, v10, v14
	v_mul_f32_e32 v9, v9, v13
	v_mul_f32_e32 v11, v11, v15
	v_bfe_u32 v12, v8, 16, 1
	v_bfe_u32 v14, v10, 16, 1
	v_bfe_u32 v13, v9, 16, 1
	v_bfe_u32 v15, v11, 16, 1
	v_add3_u32 v8, v8, v12, s26
	v_add3_u32 v10, v10, v14, s26
	v_add3_u32 v9, v9, v13, s26
	v_add3_u32 v11, v11, v15, s26
	v_lshrrev_b32_e32 v8, 16, v8
	v_lshrrev_b32_e32 v10, 16, v10
	v_and_or_b32 v8, v9, s27, v8
	v_and_or_b32 v9, v11, s27, v10
	global_store_dwordx2 v[28:29], v[8:9], off offset:1024 sc1
	global_load_dwordx4 v[8:11], v[4:5], off offset:3072
	v_mul_f32_e32 v12, v24, v7
	v_mul_f32_e32 v14, v26, v7
	v_mul_f32_e32 v13, v25, v7
	v_mul_f32_e32 v7, v27, v7
	s_waitcnt vmcnt(0)
	v_mul_f32_e32 v8, v12, v8
	v_mul_f32_e32 v10, v14, v10
	v_mul_f32_e32 v9, v13, v9
	v_mul_f32_e32 v7, v7, v11
	v_bfe_u32 v11, v8, 16, 1
	v_bfe_u32 v13, v10, 16, 1
	v_bfe_u32 v12, v9, 16, 1
	v_bfe_u32 v14, v7, 16, 1
	v_add3_u32 v8, v8, v11, s26
	v_add3_u32 v10, v10, v13, s26
	v_add3_u32 v9, v9, v12, s26
	v_add3_u32 v7, v7, v14, s26
	v_lshrrev_b32_e32 v8, 16, v8
	v_lshrrev_b32_e32 v10, 16, v10
	v_and_or_b32 v8, v9, s27, v8
	v_and_or_b32 v9, v7, s27, v10
	global_store_dwordx2 v[28:29], v[8:9], off offset:1536 sc1
	global_load_dwordx4 v[8:11], v2, s[42:43] nt
	v_lshl_add_u64 v[12:13], s[22:23], 0, v[0:1]
	s_add_u32 s22, s22, s36
	s_addc_u32 s23, s23, s37
	s_cmpk_gt_i32 s40, 0x407f
	s_waitcnt vmcnt(0)
	v_bfe_u32 v7, v8, 16, 1
	v_bfe_u32 v14, v9, 16, 1
	v_bfe_u32 v15, v10, 16, 1
	v_bfe_u32 v16, v11, 16, 1
	v_add3_u32 v7, v8, v7, s26
	v_add3_u32 v8, v9, v14, s26
	v_add3_u32 v9, v10, v15, s26
	v_add3_u32 v10, v11, v16, s26
	v_lshrrev_b32_e32 v7, 16, v7
	v_lshrrev_b32_e32 v9, 16, v9
	v_and_or_b32 v8, v8, s27, v7
	v_and_or_b32 v9, v10, s27, v9
	global_store_dwordx2 v[12:13], v[8:9], off sc1
	s_cbranch_scc0 .LBB0_33

.LBB0_36:
	s_add_i32 s4, s4, s34
	v_lshl_add_u64 v[6:7], s[6:7], 0, v[0:1]
	s_add_u32 s6, s6, s8
	s_addc_u32 s7, s7, s9
	v_lshl_add_u64 v[4:5], s[10:11], 0, v[0:1]
	s_add_u32 s10, s10, s14
	v_add_co_u32_e32 v4, vcc, 0x1b00000, v4
	s_addc_u32 s11, s11, s15
	s_nop 0
	v_addc_co_u32_e32 v5, vcc, 0, v5, vcc
	s_cmpk_gt_i32 s4, 0x40ff
	global_store_dwordx2 v[4:5], v[2:3], off sc1
	global_store_dwordx2 v[4:5], v[2:3], off offset:512 sc1
	global_store_dwordx2 v[4:5], v[2:3], off offset:1024 sc1
	global_store_dwordx2 v[4:5], v[2:3], off offset:1536 sc1
	global_store_dwordx2 v[6:7], v[2:3], off sc1
	s_cbranch_scc0 .LBB0_36
